# E8b + attention epilogue: the 8 per-row sub-LN reductions batched (hops of all rows in flight together)
# speedup vs baseline: 1.5047x; 1.0013x over previous
; DI void attn_phase(const Params& p, const u16* proj, const char* prep, u16* obuf, char* smem) {
;     ...
;     {
; #pragma unroll 1
;       for (int rr = 0; rr < 8; ++rr) {
;         const int q = wv * 8 + rr;
;         const float a0 = Ot[q * 257 + lane], a1 = Ot[q * 257 + 64 + lane], a2 = Ot[q * 257 + 128 + lane], a3 = Ot[q * 257 + 192 + lane];
;         float ss = wave_sum(a0 * a0 + a1 * a1 + a2 * a2 + a3 * a3);
;         if (lane == 0) Ot[q * 257 + 256] = rsqrtf(ss * (1.f / 256.f) + 1e-6f) * (1.f - LAM_INIT);
;       }
.LBB0_1051:
	s_waitcnt lgkmcnt(0)
	s_barrier
	v_add_u32_e32 v41, 0x404, v225
	v_add_u32_e32 v42, 0x808, v225
	v_add_u32_e32 v43, 0xc0c, v225
	v_add_u32_e32 v44, 0x1010, v225
	v_add_u32_e32 v45, 0x1414, v225
	v_add_u32_e32 v46, 0x1818, v225
	v_add_u32_e32 v47, 0x1c1c, v225
	ds_read2st64_b32 v[0:1], v225 offset1:1
	ds_read2st64_b32 v[2:3], v225 offset0:2 offset1:3
	ds_read2st64_b32 v[4:5], v41 offset1:1
	ds_read2st64_b32 v[6:7], v41 offset0:2 offset1:3
	ds_read2st64_b32 v[8:9], v42 offset1:1
	ds_read2st64_b32 v[10:11], v42 offset0:2 offset1:3
	ds_read2st64_b32 v[12:13], v43 offset1:1
	ds_read2st64_b32 v[14:15], v43 offset0:2 offset1:3
	ds_read2st64_b32 v[16:17], v44 offset1:1
	ds_read2st64_b32 v[18:19], v44 offset0:2 offset1:3
	ds_read2st64_b32 v[20:21], v45 offset1:1
	ds_read2st64_b32 v[22:23], v45 offset0:2 offset1:3
	ds_read2st64_b32 v[24:25], v46 offset1:1
	ds_read2st64_b32 v[26:27], v46 offset0:2 offset1:3
	ds_read2st64_b32 v[28:29], v47 offset1:1
	ds_read2st64_b32 v[30:31], v47 offset0:2 offset1:3
	s_waitcnt lgkmcnt(0)
	v_mul_f32_e32 v1, v1, v1
	v_fmac_f32_e32 v1, v0, v0
	v_fmac_f32_e32 v1, v2, v2
	v_fmac_f32_e32 v1, v3, v3
	v_mul_f32_e32 v5, v5, v5
	v_fmac_f32_e32 v5, v4, v4
	v_fmac_f32_e32 v5, v6, v6
	v_fmac_f32_e32 v5, v7, v7
	v_mul_f32_e32 v9, v9, v9
	v_fmac_f32_e32 v9, v8, v8
	v_fmac_f32_e32 v9, v10, v10
	v_fmac_f32_e32 v9, v11, v11
	v_mul_f32_e32 v13, v13, v13
	v_fmac_f32_e32 v13, v12, v12
	v_fmac_f32_e32 v13, v14, v14
	v_fmac_f32_e32 v13, v15, v15
	v_mul_f32_e32 v17, v17, v17
	v_fmac_f32_e32 v17, v16, v16
	v_fmac_f32_e32 v17, v18, v18
	v_fmac_f32_e32 v17, v19, v19
	v_mul_f32_e32 v21, v21, v21
	v_fmac_f32_e32 v21, v20, v20
	v_fmac_f32_e32 v21, v22, v22
	v_fmac_f32_e32 v21, v23, v23
	v_mul_f32_e32 v25, v25, v25
	v_fmac_f32_e32 v25, v24, v24
	v_fmac_f32_e32 v25, v26, v26
	v_fmac_f32_e32 v25, v27, v27
	v_mul_f32_e32 v29, v29, v29
	v_fmac_f32_e32 v29, v28, v28
	v_fmac_f32_e32 v29, v30, v30
	v_fmac_f32_e32 v29, v31, v31
	ds_bpermute_b32 v32, v181, v1
	ds_bpermute_b32 v33, v181, v5
	ds_bpermute_b32 v34, v181, v9
	ds_bpermute_b32 v35, v181, v13
	ds_bpermute_b32 v36, v181, v17
	ds_bpermute_b32 v37, v181, v21
	ds_bpermute_b32 v38, v181, v25
	ds_bpermute_b32 v39, v181, v29
	s_waitcnt lgkmcnt(0)
	v_add_f32_e32 v1, v1, v32
	v_add_f32_e32 v5, v5, v33
	v_add_f32_e32 v9, v9, v34
	v_add_f32_e32 v13, v13, v35
	v_add_f32_e32 v17, v17, v36
	v_add_f32_e32 v21, v21, v37
	v_add_f32_e32 v25, v25, v38
	v_add_f32_e32 v29, v29, v39
	ds_bpermute_b32 v32, v65, v1
	ds_bpermute_b32 v33, v65, v5
	ds_bpermute_b32 v34, v65, v9
	ds_bpermute_b32 v35, v65, v13
	ds_bpermute_b32 v36, v65, v17
	ds_bpermute_b32 v37, v65, v21
	ds_bpermute_b32 v38, v65, v25
	ds_bpermute_b32 v39, v65, v29
	s_waitcnt lgkmcnt(0)
	v_add_f32_e32 v1, v1, v32
	v_add_f32_e32 v5, v5, v33
	v_add_f32_e32 v9, v9, v34
	v_add_f32_e32 v13, v13, v35
	v_add_f32_e32 v17, v17, v36
	v_add_f32_e32 v21, v21, v37
	v_add_f32_e32 v25, v25, v38
	v_add_f32_e32 v29, v29, v39
	ds_bpermute_b32 v32, v66, v1
	ds_bpermute_b32 v33, v66, v5
	ds_bpermute_b32 v34, v66, v9
	ds_bpermute_b32 v35, v66, v13
	ds_bpermute_b32 v36, v66, v17
	ds_bpermute_b32 v37, v66, v21
	ds_bpermute_b32 v38, v66, v25
	ds_bpermute_b32 v39, v66, v29
	s_waitcnt lgkmcnt(0)
	v_add_f32_e32 v1, v1, v32
	v_add_f32_e32 v5, v5, v33
	v_add_f32_e32 v9, v9, v34
	v_add_f32_e32 v13, v13, v35
	v_add_f32_e32 v17, v17, v36
	v_add_f32_e32 v21, v21, v37
	v_add_f32_e32 v25, v25, v38
	v_add_f32_e32 v29, v29, v39
	ds_bpermute_b32 v32, v67, v1
	ds_bpermute_b32 v33, v67, v5
	ds_bpermute_b32 v34, v67, v9
	ds_bpermute_b32 v35, v67, v13
	ds_bpermute_b32 v36, v67, v17
	ds_bpermute_b32 v37, v67, v21
	ds_bpermute_b32 v38, v67, v25
	ds_bpermute_b32 v39, v67, v29
	s_waitcnt lgkmcnt(0)
; DI void attn_phase(const Params& p, const u16* proj, const char* prep, u16* obuf, char* smem) {
;     ...
;       for (int rr = 0; rr < 8; ++rr) {
;         const int q = wv * 8 + rr;
;         const float a0 = Ot[q * 257 + lane], a1 = Ot[q * 257 + 64 + lane], a2 = Ot[q * 257 + 128 + lane], a3 = Ot[q * 257 + 192 + lane];
;         float ss = wave_sum(a0 * a0 + a1 * a1 + a2 * a2 + a3 * a3);
;         if (lane == 0) Ot[q * 257 + 256] = rsqrtf(ss * (1.f / 256.f) + 1e-6f) * (1.f - LAM_INIT);
;       }
	v_add_f32_e32 v1, v1, v32
	v_add_f32_e32 v5, v5, v33
	v_add_f32_e32 v9, v9, v34
	v_add_f32_e32 v13, v13, v35
	v_add_f32_e32 v17, v17, v36
	v_add_f32_e32 v21, v21, v37
	v_add_f32_e32 v25, v25, v38
	v_add_f32_e32 v29, v29, v39
	ds_bpermute_b32 v32, v68, v1
	ds_bpermute_b32 v33, v68, v5
	ds_bpermute_b32 v34, v68, v9
	ds_bpermute_b32 v35, v68, v13
	ds_bpermute_b32 v36, v68, v17
	ds_bpermute_b32 v37, v68, v21
	ds_bpermute_b32 v38, v68, v25
	ds_bpermute_b32 v39, v68, v29
	s_waitcnt lgkmcnt(0)
	v_add_f32_e32 v1, v1, v32
	v_add_f32_e32 v5, v5, v33
	v_add_f32_e32 v9, v9, v34
	v_add_f32_e32 v13, v13, v35
	v_add_f32_e32 v17, v17, v36
	v_add_f32_e32 v21, v21, v37
	v_add_f32_e32 v25, v25, v38
	v_add_f32_e32 v29, v29, v39
	ds_bpermute_b32 v32, v69, v1
	ds_bpermute_b32 v33, v69, v5
	ds_bpermute_b32 v34, v69, v9
	ds_bpermute_b32 v35, v69, v13
	ds_bpermute_b32 v36, v69, v17
	ds_bpermute_b32 v37, v69, v21
	ds_bpermute_b32 v38, v69, v25
	ds_bpermute_b32 v39, v69, v29
	s_waitcnt lgkmcnt(0)
	v_add_f32_e32 v1, v1, v32
	v_add_f32_e32 v5, v5, v33
	v_add_f32_e32 v9, v9, v34
	v_add_f32_e32 v13, v13, v35
	v_add_f32_e32 v17, v17, v36
	v_add_f32_e32 v21, v21, v37
	v_add_f32_e32 v25, v25, v38
	v_add_f32_e32 v29, v29, v39
	s_and_saveexec_b64 s[10:11], s[8:9]
	s_mov_b32 s13, 0x800000
	v_mov_b32_e32 v48, s5
	v_fmamk_f32 v1, v1, 0x3b800000, v227
	v_mul_f32_e32 v0, 0x4b800000, v1
	v_cmp_gt_f32_e32 vcc, s13, v1
	s_nop 1
	v_cndmask_b32_e32 v1, v1, v0, vcc
	v_rsq_f32_e32 v1, v1
	s_nop 0
	v_mul_f32_e32 v0, 0x45800000, v1
	v_cndmask_b32_e32 v1, v1, v0, vcc
	v_mul_f32_e32 v1, 0x3f077f5a, v1
	ds_write_b32 v48, v1
	v_fmamk_f32 v5, v5, 0x3b800000, v227
	v_mul_f32_e32 v4, 0x4b800000, v5
	v_cmp_gt_f32_e32 vcc, s13, v5
	s_nop 1
	v_cndmask_b32_e32 v5, v5, v4, vcc
	v_rsq_f32_e32 v5, v5
	s_nop 0
	v_mul_f32_e32 v4, 0x45800000, v5
	v_cndmask_b32_e32 v5, v5, v4, vcc
	v_mul_f32_e32 v5, 0x3f077f5a, v5
	ds_write_b32 v48, v5 offset:1028
	v_fmamk_f32 v9, v9, 0x3b800000, v227
	v_mul_f32_e32 v8, 0x4b800000, v9
	v_cmp_gt_f32_e32 vcc, s13, v9
	s_nop 1
	v_cndmask_b32_e32 v9, v9, v8, vcc
	v_rsq_f32_e32 v9, v9
	s_nop 0
	v_mul_f32_e32 v8, 0x45800000, v9
	v_cndmask_b32_e32 v9, v9, v8, vcc
	v_mul_f32_e32 v9, 0x3f077f5a, v9
	ds_write_b32 v48, v9 offset:2056
	v_fmamk_f32 v13, v13, 0x3b800000, v227
	v_mul_f32_e32 v12, 0x4b800000, v13
	v_cmp_gt_f32_e32 vcc, s13, v13
	s_nop 1
	v_cndmask_b32_e32 v13, v13, v12, vcc
	v_rsq_f32_e32 v13, v13
	s_nop 0
	v_mul_f32_e32 v12, 0x45800000, v13
	v_cndmask_b32_e32 v13, v13, v12, vcc
	v_mul_f32_e32 v13, 0x3f077f5a, v13
	ds_write_b32 v48, v13 offset:3084
	v_fmamk_f32 v17, v17, 0x3b800000, v227
	v_mul_f32_e32 v16, 0x4b800000, v17
	v_cmp_gt_f32_e32 vcc, s13, v17
	s_nop 1
	v_cndmask_b32_e32 v17, v17, v16, vcc
	v_rsq_f32_e32 v17, v17
	s_nop 0
	v_mul_f32_e32 v16, 0x45800000, v17
	v_cndmask_b32_e32 v17, v17, v16, vcc
	v_mul_f32_e32 v17, 0x3f077f5a, v17
	ds_write_b32 v48, v17 offset:4112
	v_fmamk_f32 v21, v21, 0x3b800000, v227
	v_mul_f32_e32 v20, 0x4b800000, v21
	v_cmp_gt_f32_e32 vcc, s13, v21
	s_nop 1
	v_cndmask_b32_e32 v21, v21, v20, vcc
	v_rsq_f32_e32 v21, v21
	s_nop 0
	v_mul_f32_e32 v20, 0x45800000, v21
	v_cndmask_b32_e32 v21, v21, v20, vcc
	v_mul_f32_e32 v21, 0x3f077f5a, v21
	ds_write_b32 v48, v21 offset:5140
	v_fmamk_f32 v25, v25, 0x3b800000, v227
	v_mul_f32_e32 v24, 0x4b800000, v25
	v_cmp_gt_f32_e32 vcc, s13, v25
	s_nop 1
	v_cndmask_b32_e32 v25, v25, v24, vcc
	v_rsq_f32_e32 v25, v25
	s_nop 0
	v_mul_f32_e32 v24, 0x45800000, v25
	v_cndmask_b32_e32 v25, v25, v24, vcc
	v_mul_f32_e32 v25, 0x3f077f5a, v25
	ds_write_b32 v48, v25 offset:6168
	v_fmamk_f32 v29, v29, 0x3b800000, v227
	v_mul_f32_e32 v28, 0x4b800000, v29
	v_cmp_gt_f32_e32 vcc, s13, v29
	s_nop 1
	v_cndmask_b32_e32 v29, v29, v28, vcc
	v_rsq_f32_e32 v29, v29
	s_nop 0
	v_mul_f32_e32 v28, 0x45800000, v29
	v_cndmask_b32_e32 v29, v29, v28, vcc
	v_mul_f32_e32 v29, 0x3f077f5a, v29
	ds_write_b32 v48, v29 offset:7196
	s_or_b64 exec, exec, s[10:11]
